# hg_scan: dropped the four inline s_nop pairs before the MFMA waits (size-compensated locally)
# baseline (speedup 1.0000x reference)
.LBB0_336:
	s_nop 2
	ds_read_b128 v[88:91], v81 offset:34816
	ds_read_b128 v[92:95], v81 offset:34880
	ds_read_b128 v[96:99], v32
	ds_read_b128 v[32:35], v32 offset:64
	ds_read_b128 v[100:103], v71
	ds_read_b128 v[104:107], v72
	s_add_u32 s38, s38, 0x4000
	s_waitcnt lgkmcnt(3)
	v_mfma_f32_16x16x32_bf16 v[88:91], v[88:91], v[96:99], 0
	s_addc_u32 s39, s39, 0
	v_add_u32_e32 v2, 0x38000, v2
	v_lshl_add_u64 v[52:53], v[52:53], 0, s[30:31]
	s_waitcnt lgkmcnt(2)
	v_mfma_f32_16x16x32_bf16 v[32:35], v[92:95], v[32:35], v[88:91]
	s_cmp_eq_u32 s38, 0x80000
	v_lshl_add_u64 v[58:59], v[58:59], 0, s[34:35]
	s_waitcnt lgkmcnt(0)
	s_barrier
	s_nop 3
	v_pk_mul_f32 v[34:35], v[34:35], v[106:107]
	v_pk_mul_f32 v[32:33], v[32:33], v[104:105]
	v_pk_fma_f32 v[62:63], v[62:63], v[102:103], v[34:35]
	v_pk_fma_f32 v[60:61], v[60:61], v[100:101], v[32:33]
	s_cbranch_scc1 .LBB0_332

.LBB0_343:
	s_waitcnt lgkmcnt(0)
	s_barrier
	ds_read_b128 v[32:35], v67
	s_waitcnt lgkmcnt(0)
	v_pk_mul_f32 v[34:35], v[62:63], v[34:35]
	v_pk_mul_f32 v[32:33], v[60:61], v[32:33]
	v_and_b32_sdwa v87, v34, v83 dst_sel:DWORD dst_unused:UNUSED_PAD src0_sel:WORD_1 src1_sel:DWORD
	v_and_b32_sdwa v88, v32, v83 dst_sel:DWORD dst_unused:UNUSED_PAD src0_sel:WORD_1 src1_sel:DWORD
	v_add3_u32 v32, v32, v88, s51
	v_add3_u32 v34, v34, v87, s51
	v_and_b32_sdwa v87, v35, v83 dst_sel:DWORD dst_unused:UNUSED_PAD src0_sel:WORD_1 src1_sel:DWORD
	v_and_b32_sdwa v88, v33, v83 dst_sel:DWORD dst_unused:UNUSED_PAD src0_sel:WORD_1 src1_sel:DWORD
	v_add3_u32 v35, v35, v87, s51
	v_add3_u32 v33, v33, v88, s51
	v_and_b32_e32 v35, 0xffff0000, v35
	v_and_b32_e32 v87, 0xffff0000, v33
	v_or_b32_sdwa v33, v35, v34 dst_sel:DWORD dst_unused:UNUSED_PAD src0_sel:DWORD src1_sel:WORD_1
	v_or_b32_sdwa v32, v87, v32 dst_sel:DWORD dst_unused:UNUSED_PAD src0_sel:DWORD src1_sel:WORD_1
	ds_write_b64 v77, v[32:33]
	ds_read_b128 v[32:35], v84
	ds_read_b128 v[88:91], v84 offset:64
	ds_read_b128 v[92:95], v78 offset:17408
	ds_read_b128 v[96:99], v78 offset:17472
	s_waitcnt lgkmcnt(1)
	v_mfma_f32_16x16x32_bf16 v[32:35], v[32:35], v[92:95], 0
	ds_read_b128 v[92:95], v84 offset:128
	s_waitcnt lgkmcnt(1)
	v_mfma_f32_16x16x32_bf16 v[32:35], v[88:91], v[96:99], v[32:35]
	ds_read_b128 v[88:91], v84 offset:192
	ds_read_b128 v[96:99], v78 offset:17536
	ds_read_b128 v[100:103], v78 offset:17600
	s_waitcnt lgkmcnt(1)
	v_mfma_f32_16x16x32_bf16 v[32:35], v[92:95], v[96:99], v[32:35]
	s_waitcnt lgkmcnt(0)
	v_mfma_f32_16x16x32_bf16 v[32:35], v[88:91], v[100:103], v[32:35]
	s_nop 7
	v_cndmask_b32_e64 v32, 0, v32, s[6:7]
	v_bfe_u32 v87, v32, 16, 1
	v_add3_u32 v32, v32, v87, s51
	v_lshrrev_b32_e32 v32, 16, v32
	v_mov_b32_e32 v87, 0
	s_nop 1
	v_mov_b32_dpp v87, v32 quad_perm:[1,0,3,2] row_mask:0xf bank_mask:0xf
	s_and_saveexec_b64 s[40:41], s[2:3]
	v_lshl_or_b32 v32, v87, 16, v32
	ds_write_b32 v85, v32 offset:53248
	s_or_b64 exec, exec, s[40:41]
	v_cndmask_b32_e64 v32, 0, v33, s[8:9]
	v_bfe_u32 v33, v32, 16, 1
	v_add3_u32 v32, v32, v33, s51
	v_lshrrev_b32_e32 v87, 16, v32
	v_mov_b32_e32 v33, 0
	s_nop 1
	v_mov_b32_dpp v33, v87 quad_perm:[1,0,3,2] row_mask:0xf bank_mask:0xf
	s_and_saveexec_b64 s[40:41], s[4:5]
	v_and_or_b32 v32, v32, s52, v33
	ds_write_b32 v85, v32 offset:53392
	s_or_b64 exec, exec, s[40:41]
	v_cndmask_b32_e64 v32, 0, v34, s[10:11]
	v_bfe_u32 v33, v32, 16, 1
	v_add3_u32 v32, v32, v33, s51
	v_lshrrev_b32_e32 v32, 16, v32
	v_mov_b32_e32 v33, 0
	s_nop 1
	v_mov_b32_dpp v33, v32 quad_perm:[1,0,3,2] row_mask:0xf bank_mask:0xf
	s_and_saveexec_b64 s[40:41], s[2:3]
	v_lshl_or_b32 v32, v33, 16, v32
	ds_write_b32 v85, v32 offset:53536
	s_or_b64 exec, exec, s[40:41]
	v_cndmask_b32_e64 v32, 0, v35, s[12:13]
	v_bfe_u32 v33, v32, 16, 1
	v_add3_u32 v32, v32, v33, s51
	v_lshrrev_b32_e32 v34, 16, v32
	v_mov_b32_e32 v33, 0
	s_nop 1
	v_mov_b32_dpp v33, v34 quad_perm:[1,0,3,2] row_mask:0xf bank_mask:0xf
	s_and_saveexec_b64 s[40:41], s[4:5]
	v_and_or_b32 v32, v32, s52, v33
	ds_write_b32 v85, v32 offset:53680
	s_or_b64 exec, exec, s[40:41]
	ds_read_b128 v[32:35], v84
	ds_read_b128 v[88:91], v84 offset:64
	ds_read_b128 v[92:95], v79 offset:17408
	ds_read_b128 v[96:99], v79 offset:17472
	s_waitcnt lgkmcnt(1)
	v_mfma_f32_16x16x32_bf16 v[32:35], v[32:35], v[92:95], 0
	ds_read_b128 v[92:95], v84 offset:128
	ds_read_b128 v[100:103], v84 offset:192
	s_waitcnt lgkmcnt(2)
	v_mfma_f32_16x16x32_bf16 v[32:35], v[88:91], v[96:99], v[32:35]
	ds_read_b128 v[88:91], v79 offset:17536
	ds_read_b128 v[96:99], v79 offset:17600
	s_waitcnt lgkmcnt(1)
	v_mfma_f32_16x16x32_bf16 v[32:35], v[92:95], v[88:91], v[32:35]
	s_waitcnt lgkmcnt(0)
	v_mfma_f32_16x16x32_bf16 v[32:35], v[100:103], v[96:99], v[32:35]
	s_nop 7
	v_cndmask_b32_e64 v32, 0, v32, s[14:15]
	v_bfe_u32 v87, v32, 16, 1
	v_add3_u32 v32, v32, v87, s51
	v_lshrrev_b32_e32 v32, 16, v32
	v_mov_b32_e32 v87, 0
	s_nop 1
	v_mov_b32_dpp v87, v32 quad_perm:[1,0,3,2] row_mask:0xf bank_mask:0xf
	s_and_saveexec_b64 s[40:41], s[2:3]
	v_lshl_or_b32 v32, v87, 16, v32
	ds_write_b32 v86, v32 offset:53248
	s_or_b64 exec, exec, s[40:41]
	v_cndmask_b32_e64 v32, 0, v33, s[16:17]
	v_bfe_u32 v33, v32, 16, 1
	v_add3_u32 v32, v32, v33, s51
	v_lshrrev_b32_e32 v87, 16, v32
	v_mov_b32_e32 v33, 0
	s_nop 1
	v_mov_b32_dpp v33, v87 quad_perm:[1,0,3,2] row_mask:0xf bank_mask:0xf
	s_and_saveexec_b64 s[40:41], s[4:5]
	v_and_or_b32 v32, v32, s52, v33
	ds_write_b32 v86, v32 offset:53392
	s_or_b64 exec, exec, s[40:41]
	v_cndmask_b32_e64 v32, 0, v34, s[18:19]
	v_bfe_u32 v33, v32, 16, 1
	v_add3_u32 v32, v32, v33, s51
	v_lshrrev_b32_e32 v32, 16, v32
	v_mov_b32_e32 v33, 0
	s_nop 1
	v_mov_b32_dpp v33, v32 quad_perm:[1,0,3,2] row_mask:0xf bank_mask:0xf
	s_and_saveexec_b64 s[40:41], s[2:3]
	v_lshl_or_b32 v32, v33, 16, v32
	ds_write_b32 v86, v32 offset:53536
	s_or_b64 exec, exec, s[40:41]
	v_cndmask_b32_e64 v32, 0, v35, s[20:21]
	v_bfe_u32 v33, v32, 16, 1
	v_add3_u32 v32, v32, v33, s51
	v_lshrrev_b32_e32 v34, 16, v32
	v_mov_b32_e32 v33, 0
	s_nop 1
	v_mov_b32_dpp v33, v34 quad_perm:[1,0,3,2] row_mask:0xf bank_mask:0xf
	s_and_saveexec_b64 s[40:41], s[4:5]
	v_and_or_b32 v32, v32, s52, v33
	ds_write_b32 v86, v32 offset:53680
	s_or_b64 exec, exec, s[40:41]
	s_and_b64 vcc, exec, s[28:29]
	v_add_u32_e32 v32, v66, v69
	s_waitcnt lgkmcnt(0)
	s_barrier
	s_cbranch_vccz .LBB0_336
	v_add_u32_e32 v33, v70, v69
	ds_read_b128 v[88:91], v33
	v_add_u32_e32 v34, v68, v69
	ds_read_b128 v[92:95], v33 offset:64
	ds_read_b128 v[96:99], v34
	ds_read_b128 v[100:103], v34 offset:64
	s_waitcnt lgkmcnt(1)
	v_mfma_f32_16x16x32_bf16 v[88:91], v[88:91], v[96:99], 0
	ds_read_b128 v[96:99], v33 offset:128
	ds_read_b128 v[104:107], v33 offset:192
	s_waitcnt lgkmcnt(2)
	v_mfma_f32_16x16x32_bf16 v[88:91], v[92:95], v[100:103], v[88:91]
	ds_read_b128 v[92:95], v34 offset:128
	ds_read_b128 v[100:103], v34 offset:192
	s_waitcnt lgkmcnt(1)
	v_mfma_f32_16x16x32_bf16 v[88:91], v[96:99], v[92:95], v[88:91]
	ds_read_b128 v[92:95], v80 offset:53248
	ds_read_b128 v[96:99], v80 offset:53312
	s_waitcnt lgkmcnt(2)
	v_mfma_f32_16x16x32_bf16 v[88:91], v[104:107], v[100:103], v[88:91]
	ds_read_b128 v[100:103], v32
	ds_read_b128 v[104:107], v32 offset:64
	s_waitcnt lgkmcnt(1)
	v_mfma_f32_16x16x32_bf16 v[88:91], v[92:95], v[100:103], v[88:91]
	s_waitcnt lgkmcnt(0)
	v_mfma_f32_16x16x32_bf16 v[88:91], v[96:99], v[104:107], v[88:91]
	s_nop 7
	global_store_dword v[58:59], v88, off
	global_store_dword v[58:59], v89, off offset:64
	global_store_dword v[58:59], v90, off offset:128
	global_store_dword v[58:59], v91, off offset:192
	s_branch .LBB0_336

.LBB0_364:
	s_sext_i32_i8 s3, s4
	s_lshl_b32 s2, s2, 3
	s_add_i32 s6, s2, s3
	s_add_u32 s49, s1, 0x2000000
	s_addc_u32 s51, s5, 0
	s_mov_b64 s[4:5], 0x80
	s_add_i32 m0, s45, 0x18000
	v_lshl_add_u64 v[14:15], v[14:15], 0, s[4:5]
	s_waitcnt vmcnt(2)
	s_barrier
	global_load_lds_dwordx4 v[14:15], off
	v_lshl_add_u64 v[12:13], v[12:13], 0, s[4:5]
	s_add_i32 m0, s45, 0x1a000
	s_add_i32 s52, s45, 0x8000
	s_add_i32 s53, s45, 0xa000
	global_load_lds_dwordx4 v[12:13], off
	v_lshl_add_u64 v[8:9], v[8:9], 0, s[4:5]
	s_mov_b32 m0, s52
	s_add_u32 s2, s38, 0x80080
	global_load_lds_dwordx4 v[8:9], off
	v_lshl_add_u64 v[8:9], v[10:11], 0, s[4:5]
	s_mov_b32 m0, s53
	s_addc_u32 s3, s39, 0
	global_load_lds_dwordx4 v[8:9], off
	s_add_i32 m0, s45, 0x1c000
	v_lshl_add_u64 v[8:9], s[2:3], 0, v[4:5]
	global_load_lds_dwordx4 v[8:9], off
	v_lshl_add_u64 v[8:9], s[2:3], 0, v[0:1]
	s_add_i32 m0, s45, 0x1e000
	s_sext_i32_i8 s7, s0
	global_load_lds_dwordx4 v[8:9], off
	v_and_b32_e32 v8, 15, v16
	v_readlane_b32 s0, v247, 6
	v_and_b32_e32 v11, 48, v16
	v_lshrrev_b32_e32 v9, 6, v16
	v_or_b32_e32 v14, s0, v8
	v_lshlrev_b32_e32 v10, 6, v14
	s_movk_i32 s0, 0x3c0
	v_and_or_b32 v10, v10, s0, v11
	v_readlane_b32 s0, v247, 8
	v_lshlrev_b32_e32 v13, 2, v14
	v_and_b32_e32 v13, 32, v13
	v_lshl_add_u32 v12, v9, 10, s0
	v_bitop3_b32 v13, v10, v12, v13 bitop3:0xde
	v_readlane_b32 s0, v247, 10
	v_lshlrev_b32_e32 v10, 2, v16
	v_lshl_or_b32 v8, v8, 6, v11
	v_add_lshl_u32 v9, v9, s0, 10
	v_and_b32_e32 v10, 32, v10
	v_bitop3_b32 v15, v8, v9, v10 bitop3:0xde
	v_lshrrev_b32_e32 v8, 2, v16
	s_waitcnt vmcnt(6)
	v_and_b32_e32 v8, 28, v8
	v_readlane_b32 s0, v247, 9
	s_add_i32 s57, 0, 0x10000
	s_add_i32 s58, 0, 0x14000
	v_add_u32_e32 v12, s0, v8
	s_ashr_i32 s54, s76, 31
	s_mov_b32 s55, s76
	s_add_i32 s56, s80, s76
	v_mov_b64_e32 v[8:9], 0x80
	v_mov_b64_e32 v[10:11], 0x7f
	v_add_u32_e32 v16, s57, v15
	v_add_u32_e32 v17, s58, v15
	v_add_u32_e32 v18, 0, v13
	s_mov_b64 s[8:9], 0x100
	s_mov_b64 s[10:11], 0x180
	v_lshlrev_b32_e32 v12, 2, v12
	v_mov_b32_e32 v13, v5
	s_mov_b64 s[12:13], 0xc000
	s_mov_b64 s[14:15], 0x20000
	s_mov_b32 s59, 0x20000
	s_mov_b64 s[16:17], 0x24000
	s_mov_b32 s60, 0x24000
	s_mov_b64 s[18:19], 0x28000
	s_mov_b32 s61, 0x28000
	s_mov_b64 s[20:21], 0x2c000
	s_mov_b64 s[24:25], s[80:81]
	s_barrier
	s_branch .LBB0_366
	s_nop 0
	s_nop 0
	s_nop 0
	s_nop 0
	s_nop 0
	s_nop 0
	s_nop 0
	s_nop 0
